# v53 plus ssd_passC epilogue xor-1/2/4 sums on DPP instead of ds_bpermute
# baseline (speedup 1.0000x reference)
.LBB0_243:
	ds_read_b128 v[34:37], v113
	ds_read_b128 v[116:119], v113 offset:32
	ds_read2_b32 v[102:103], v114 offset1:1
	v_cmp_le_u32_e32 vcc, v115, v100
	v_or_b32_e32 v125, 3, v115
	s_waitcnt lgkmcnt(0)
	v_mfma_f32_32x32x16_bf16 v[34:49], v[34:37], v[90:93], 0
	v_or_b32_e32 v126, 2, v115
	v_sub_f32_e32 v102, v110, v102
	v_mul_f32_e32 v102, 0x3fb8aa3b, v102
	v_exp_f32_e32 v102, v102
	v_or_b32_e32 v127, 9, v115
	v_or_b32_e32 v128, 8, v115
	v_or_b32_e32 v129, 11, v115
	v_mfma_f32_32x32x16_bf16 v[34:49], v[116:119], v[94:97], v[34:49]
	ds_read_b128 v[116:119], v113 offset:64
	v_or_b32_e32 v130, 10, v115
	v_or_b32_e32 v120, 25, v115
	v_or_b32_e32 v121, 24, v115
	v_or_b32_e32 v122, 26, v115
	s_add_i32 s3, s3, -1
	v_add_u32_e32 v114, 0x80, v114
	s_cmp_lg_u32 s3, 0
	s_waitcnt lgkmcnt(0)
	v_mfma_f32_32x32x16_bf16 v[34:49], v[116:119], v[78:81], v[34:49]
	ds_read_b128 v[116:119], v113 offset:96
	s_waitcnt lgkmcnt(0)
	v_mfma_f32_32x32x16_bf16 v[34:49], v[116:119], v[74:77], v[34:49]
	ds_read_b128 v[116:119], v113 offset:128
	s_waitcnt lgkmcnt(0)
	v_mfma_f32_32x32x16_bf16 v[34:49], v[116:119], v[66:69], v[34:49]
	ds_read_b128 v[116:119], v113 offset:160
	s_waitcnt lgkmcnt(0)
	v_mfma_f32_32x32x16_bf16 v[34:49], v[116:119], v[70:73], v[34:49]
	ds_read_b128 v[116:119], v113 offset:192
	s_waitcnt lgkmcnt(0)
	v_mfma_f32_32x32x16_bf16 v[34:49], v[116:119], v[82:85], v[34:49]
	ds_read_b128 v[116:119], v113 offset:224
	v_add_u32_e32 v113, 0x2200, v113
	s_waitcnt lgkmcnt(0)
	v_mfma_f32_32x32x16_bf16 v[34:49], v[116:119], v[86:89], v[34:49]
	v_or_b32_e32 v116, 17, v115
	v_or_b32_e32 v117, 16, v115
	v_or_b32_e32 v118, 19, v115
	v_or_b32_e32 v119, 18, v115
	s_nop 7
	v_mul_f32_e32 v34, v34, v102
	v_cndmask_b32_e32 v123, 0, v34, vcc
	v_sub_f32_e32 v34, v110, v103
	v_mul_f32_e32 v34, 0x3fb8aa3b, v34
	v_exp_f32_e32 v34, v34
	v_cmp_lt_u32_e32 vcc, v115, v100
	v_mul_f32_e32 v34, v35, v34
	s_nop 0
	v_cndmask_b32_e32 v124, 0, v34, vcc
	v_add_u32_e32 v34, s2, v126
	v_add_u32_e32 v35, s2, v125
	v_lshl_add_u32 v34, v34, 2, v101
	v_lshl_add_u32 v35, v35, 2, v101
	ds_read_b32 v34, v34 offset:2048
	ds_read_b32 v35, v35 offset:2048
	v_cmp_le_u32_e32 vcc, v126, v100
	v_cvt_pk_bf16_f32 v124, v123, v124
	s_waitcnt lgkmcnt(0)
	v_sub_f32_e32 v34, v110, v34
	v_sub_f32_e32 v35, v110, v35
	v_mul_f32_e32 v34, 0x3fb8aa3b, v34
	v_mul_f32_e32 v35, 0x3fb8aa3b, v35
	v_exp_f32_e32 v34, v34
	v_exp_f32_e32 v35, v35
	s_nop 0
	v_pk_mul_f32 v[34:35], v[36:37], v[34:35]
	v_add_u32_e32 v36, s2, v128
	v_add_u32_e32 v37, s2, v127
	v_lshl_add_u32 v36, v36, 2, v101
	v_lshl_add_u32 v37, v37, 2, v101
	ds_read_b32 v36, v36 offset:2048
	ds_read_b32 v37, v37 offset:2048
	v_cvt_pk_bf16_f32 v34, v34, v35
	v_cndmask_b32_e32 v35, 0, v34, vcc
	v_lshrrev_b32_e32 v34, 16, v34
	s_waitcnt lgkmcnt(0)
	v_sub_f32_e32 v36, v110, v36
	v_sub_f32_e32 v37, v110, v37
	v_mul_f32_e32 v36, 0x3fb8aa3b, v36
	v_mul_f32_e32 v37, 0x3fb8aa3b, v37
	v_exp_f32_e32 v36, v36
	v_exp_f32_e32 v37, v37
	v_cmp_le_u32_e32 vcc, v125, v99
	v_pk_mul_f32 v[36:37], v[38:39], v[36:37]
	v_add_u32_e32 v38, s2, v130
	v_add_u32_e32 v39, s2, v129
	v_lshl_add_u32 v38, v38, 2, v101
	v_lshl_add_u32 v39, v39, 2, v101
	ds_read_b32 v38, v38 offset:2048
	ds_read_b32 v39, v39 offset:2048
	v_cndmask_b32_e32 v34, 0, v34, vcc
	v_perm_b32 v125, v34, v35, s17
	v_cvt_pk_bf16_f32 v34, v36, v37
	s_waitcnt lgkmcnt(0)
	v_sub_f32_e32 v38, v110, v38
	v_sub_f32_e32 v39, v110, v39
	v_mul_f32_e32 v38, 0x3fb8aa3b, v38
	v_mul_f32_e32 v39, 0x3fb8aa3b, v39
	v_exp_f32_e32 v38, v38
	v_exp_f32_e32 v39, v39
	v_cmp_le_u32_e32 vcc, v128, v100
	v_pk_mul_f32 v[102:103], v[40:41], v[38:39]
	v_add_u32_e32 v38, s2, v117
	v_add_u32_e32 v39, s2, v116
	v_lshl_add_u32 v38, v38, 2, v101
	v_lshl_add_u32 v39, v39, 2, v101
	ds_read_b32 v38, v38 offset:2048
	ds_read_b32 v39, v39 offset:2048
	v_add_u32_e32 v40, s2, v119
	v_add_u32_e32 v41, s2, v118
	v_lshl_add_u32 v40, v40, 2, v101
	v_lshl_add_u32 v41, v41, 2, v101
	ds_read_b32 v40, v40 offset:2048
	ds_read_b32 v41, v41 offset:2048
	s_waitcnt lgkmcnt(0)
	v_sub_f32_e32 v38, v110, v38
	v_sub_f32_e32 v39, v110, v39
	v_mul_f32_e32 v38, 0x3fb8aa3b, v38
	v_mul_f32_e32 v39, 0x3fb8aa3b, v39
	v_exp_f32_e32 v38, v38
	v_exp_f32_e32 v39, v39
	v_sub_f32_e32 v40, v110, v40
	v_sub_f32_e32 v41, v110, v41
	v_mul_f32_e32 v40, 0x3fb8aa3b, v40
	v_pk_mul_f32 v[38:39], v[42:43], v[38:39]
	v_mul_f32_e32 v41, 0x3fb8aa3b, v41
	v_add_u32_e32 v42, s2, v121
	v_add_u32_e32 v43, s2, v120
	v_exp_f32_e32 v40, v40
	v_exp_f32_e32 v41, v41
	v_lshl_add_u32 v42, v42, 2, v101
	v_lshl_add_u32 v43, v43, 2, v101
	ds_read_b32 v42, v42 offset:2048
	ds_read_b32 v43, v43 offset:2048
	v_pk_mul_f32 v[40:41], v[44:45], v[40:41]
	v_add_u32_e32 v44, s2, v122
	v_lshl_add_u32 v44, v44, 2, v101
	ds_read_b32 v44, v44 offset:2048
	s_waitcnt lgkmcnt(0)
	v_sub_f32_e32 v42, v110, v42
	v_sub_f32_e32 v43, v110, v43
	v_mul_f32_e32 v42, 0x3fb8aa3b, v42
	v_mul_f32_e32 v43, 0x3fb8aa3b, v43
	v_exp_f32_e32 v42, v42
	v_exp_f32_e32 v43, v43
	v_cndmask_b32_e32 v35, 0, v34, vcc
	v_lshrrev_b32_e32 v34, 16, v34
	v_cmp_le_u32_e32 vcc, v127, v99
	v_pk_mul_f32 v[42:43], v[46:47], v[42:43]
	v_or_b32_e32 v46, 27, v115
	v_add_u32_e32 v45, s2, v46
	v_lshl_add_u32 v45, v45, 2, v101
	ds_read_b32 v45, v45 offset:2048
	v_cndmask_b32_e32 v34, 0, v34, vcc
	v_perm_b32 v126, v34, v35, s17
	v_cvt_pk_bf16_f32 v34, v102, v103
	v_cmp_le_u32_e32 vcc, v130, v100
	v_cvt_pk_bf16_f32 v38, v38, v39
	v_sub_f32_e32 v44, v110, v44
	v_cndmask_b32_e32 v35, 0, v34, vcc
	v_lshrrev_b32_e32 v34, 16, v34
	v_cmp_le_u32_e32 vcc, v129, v99
	s_waitcnt lgkmcnt(0)
	v_sub_f32_e32 v45, v110, v45
	v_mul_f32_e32 v44, 0x3fb8aa3b, v44
	v_cndmask_b32_e32 v34, 0, v34, vcc
	v_cmp_le_u32_e32 vcc, v117, v100
	v_perm_b32 v127, v34, v35, s17
	ds_read2_b64 v[128:131], v112 offset1:2
	ds_read2_b64 v[34:37], v112 offset0:4 offset1:6
	v_cndmask_b32_e32 v39, 0, v38, vcc
	v_lshrrev_b32_e32 v38, 16, v38
	v_cmp_le_u32_e32 vcc, v116, v99
	v_mul_f32_e32 v45, 0x3fb8aa3b, v45
	v_exp_f32_e32 v44, v44
	v_cndmask_b32_e32 v38, 0, v38, vcc
	v_perm_b32 v38, v38, v39, s17
	v_cvt_pk_bf16_f32 v39, v40, v41
	v_cmp_le_u32_e32 vcc, v119, v100
	v_exp_f32_e32 v45, v45
	v_add_u32_e32 v47, 0x2000, v112
	v_cndmask_b32_e32 v40, 0, v39, vcc
	v_lshrrev_b32_e32 v39, 16, v39
	v_cmp_le_u32_e32 vcc, v118, v99
	s_waitcnt lgkmcnt(0)
	v_mfma_f32_32x32x16_bf16 v[2:17], v[128:131], v[124:127], v[2:17]
	ds_read2_b64 v[128:131], v47 offset0:64 offset1:66
	v_cndmask_b32_e32 v39, 0, v39, vcc
	v_perm_b32 v39, v39, v40, s17
	v_cvt_pk_bf16_f32 v40, v42, v43
	v_cmp_le_u32_e32 vcc, v121, v100
	v_pk_mul_f32 v[44:45], v[48:49], v[44:45]
	v_add_u32_e32 v112, 64, v112
	v_cndmask_b32_e32 v41, 0, v40, vcc
	v_lshrrev_b32_e32 v40, 16, v40
	v_cmp_le_u32_e32 vcc, v120, v99
	s_waitcnt lgkmcnt(0)
	v_mfma_f32_32x32x16_bf16 v[18:33], v[128:131], v[124:127], v[18:33]
	v_add_u32_e32 v115, 32, v115
	v_cndmask_b32_e32 v40, 0, v40, vcc
	v_perm_b32 v40, v40, v41, s17
	v_cvt_pk_bf16_f32 v41, v44, v45
	v_cmp_le_u32_e32 vcc, v122, v100
	s_nop 1
	v_cndmask_b32_e32 v42, 0, v41, vcc
	v_lshrrev_b32_e32 v41, 16, v41
	v_cmp_le_u32_e32 vcc, v46, v99
	s_nop 1
	v_cndmask_b32_e32 v41, 0, v41, vcc
	v_perm_b32 v41, v41, v42, s17
	s_nop 1
	v_mfma_f32_32x32x16_bf16 v[2:17], v[34:37], v[38:41], v[2:17]
	ds_read2_b64 v[34:37], v47 offset0:68 offset1:70
	s_waitcnt lgkmcnt(0)
	v_mfma_f32_32x32x16_bf16 v[18:33], v[34:37], v[38:41], v[18:33]
	s_cbranch_scc1 .LBB0_243
	s_lshl_b64 s[2:3], s[36:37], 2
	s_add_u32 s7, s42, s2
	s_addc_u32 s3, s43, s3
	s_add_i32 s10, s56, s54
	s_ashr_i32 s11, s10, 31
	s_ashr_i32 s2, s55, 6
	s_lshl_b64 s[10:11], s[10:11], 2
	s_add_u32 s10, s7, s10
	s_addc_u32 s11, s3, s11
	global_load_dword v48, v1, s[10:11]
	v_or_b32_e32 v34, s44, v111
	v_lshlrev_b32_e32 v34, 1, v34
	v_add3_u32 v49, v105, v109, v34
	ds_read2_b64 v[38:41], v49 offset1:2
	ds_read2_b64 v[44:47], v49 offset0:4 offset1:6
	s_mul_i32 s3, s2, 0x1200
	s_add_i32 s3, s3, 0
	s_add_i32 s3, s3, 0x1a800
	s_waitcnt lgkmcnt(0)
	v_and_b32_e32 v35, 0xffff0000, v38
	v_lshlrev_b32_e32 v34, 16, v38
	s_waitcnt vmcnt(0)
	v_pk_fma_f32 v[34:35], v[48:49], v[34:35], v[2:3] op_sel_hi:[0,1,1]
	v_and_b32_e32 v3, 0xffff0000, v39
	v_lshlrev_b32_e32 v2, 16, v39
	v_pk_fma_f32 v[36:37], v[48:49], v[2:3], v[4:5] op_sel_hi:[0,1,1]
	v_and_b32_e32 v3, 0xffff0000, v40
	v_lshlrev_b32_e32 v2, 16, v40
	v_pk_fma_f32 v[38:39], v[48:49], v[2:3], v[6:7] op_sel_hi:[0,1,1]
	v_and_b32_e32 v3, 0xffff0000, v41
	v_lshlrev_b32_e32 v2, 16, v41
	v_pk_fma_f32 v[42:43], v[48:49], v[2:3], v[8:9] op_sel_hi:[0,1,1]
	v_and_b32_e32 v3, 0xffff0000, v44
	v_lshlrev_b32_e32 v2, 16, v44
	v_pk_fma_f32 v[6:7], v[48:49], v[2:3], v[10:11] op_sel_hi:[0,1,1]
	v_and_b32_e32 v3, 0xffff0000, v45
	v_lshlrev_b32_e32 v2, 16, v45
	v_pk_fma_f32 v[12:13], v[48:49], v[2:3], v[12:13] op_sel_hi:[0,1,1]
	v_and_b32_e32 v3, 0xffff0000, v46
	v_lshlrev_b32_e32 v2, 16, v46
	v_pk_fma_f32 v[14:15], v[48:49], v[2:3], v[14:15] op_sel_hi:[0,1,1]
	v_and_b32_e32 v3, 0xffff0000, v47
	v_lshlrev_b32_e32 v2, 16, v47
	v_pk_fma_f32 v[40:41], v[48:49], v[2:3], v[16:17] op_sel_hi:[0,1,1]
	ds_read2_b64 v[2:5], v49 offset0:8 offset1:10
	v_cvt_pk_bf16_f32 v6, v6, v7
	v_cvt_pk_bf16_f32 v7, v12, v13
	v_cvt_pk_bf16_f32 v12, v14, v15
	v_cvt_pk_bf16_f32 v13, v40, v41
	s_waitcnt lgkmcnt(0)
	v_and_b32_e32 v9, 0xffff0000, v2
	v_lshlrev_b32_e32 v8, 16, v2
	v_and_b32_e32 v11, 0xffff0000, v3
	v_lshlrev_b32_e32 v10, 16, v3
	v_and_b32_e32 v3, 0xffff0000, v4
	v_lshlrev_b32_e32 v2, 16, v4
	v_pk_fma_f32 v[8:9], v[48:49], v[8:9], v[18:19] op_sel_hi:[0,1,1]
	v_pk_fma_f32 v[18:19], v[48:49], v[2:3], v[22:23] op_sel_hi:[0,1,1]
	v_and_b32_e32 v3, 0xffff0000, v5
	v_lshlrev_b32_e32 v2, 16, v5
	v_pk_fma_f32 v[22:23], v[48:49], v[2:3], v[24:25] op_sel_hi:[0,1,1]
	ds_read2_b64 v[2:5], v49 offset0:12 offset1:14
	v_pk_fma_f32 v[16:17], v[48:49], v[10:11], v[20:21] op_sel_hi:[0,1,1]
	s_waitcnt lgkmcnt(0)
	s_barrier
	v_and_b32_e32 v25, 0xffff0000, v5
	v_lshlrev_b32_e32 v24, 16, v5
	v_and_b32_e32 v11, 0xffff0000, v2
	v_lshlrev_b32_e32 v10, 16, v2
	v_and_b32_e32 v21, 0xffff0000, v3
	v_lshlrev_b32_e32 v20, 16, v3
	v_and_b32_e32 v3, 0xffff0000, v4
	v_lshlrev_b32_e32 v2, 16, v4
	v_pk_fma_f32 v[4:5], v[48:49], v[24:25], v[32:33] op_sel_hi:[0,1,1]
	v_mul_u32_u24_e32 v24, 0x90, v108
	v_add3_u32 v0, s3, v24, v0
	v_pk_fma_f32 v[10:11], v[48:49], v[10:11], v[26:27] op_sel_hi:[0,1,1]
	v_pk_fma_f32 v[20:21], v[48:49], v[20:21], v[28:29] op_sel_hi:[0,1,1]
	v_pk_fma_f32 v[2:3], v[48:49], v[2:3], v[30:31] op_sel_hi:[0,1,1]
	ds_write2_b64 v0, v[6:7], v[12:13] offset0:4 offset1:6
	v_cvt_pk_bf16_f32 v6, v8, v9
	v_cvt_pk_bf16_f32 v7, v16, v17
	v_cvt_pk_bf16_f32 v8, v18, v19
	v_cvt_pk_bf16_f32 v9, v22, v23
	ds_write2_b64 v0, v[6:7], v[8:9] offset0:8 offset1:10
	v_cvt_pk_bf16_f32 v6, v10, v11
	v_cvt_pk_bf16_f32 v7, v20, v21
	v_cvt_pk_bf16_f32 v2, v2, v3
	v_cvt_pk_bf16_f32 v3, v4, v5
	v_cvt_pk_bf16_f32 v24, v34, v35
	v_cvt_pk_bf16_f32 v25, v36, v37
	v_cvt_pk_bf16_f32 v26, v38, v39
	v_cvt_pk_bf16_f32 v27, v42, v43
	ds_write2_b64 v0, v[6:7], v[2:3] offset0:12 offset1:14
	v_and_b32_e32 v2, 64, v174
	ds_write2_b64 v0, v[24:25], v[26:27] offset1:2
	v_xor_b32_e32 v0, 1, v174
	v_add_u32_e32 v2, 64, v2
	v_cmp_lt_i32_e32 vcc, v0, v2
	v_lshl_add_u32 v18, v98, 1, s3
	s_waitcnt lgkmcnt(0)
	v_and_b32_e32 v12, 0xffff0000, v62
	v_cndmask_b32_e32 v0, v174, v0, vcc
	v_lshlrev_b32_e32 v8, 2, v0
	v_xor_b32_e32 v0, 2, v174
	v_cmp_lt_i32_e32 vcc, v0, v2
	v_mul_f32_e32 v11, 0xbfb8aa3b, v12
	v_exp_f32_e32 v11, v11
	v_cndmask_b32_e32 v0, v174, v0, vcc
	v_lshlrev_b32_e32 v9, 2, v0
	v_xor_b32_e32 v0, 4, v174
	v_cmp_lt_i32_e32 vcc, v0, v2
	v_mad_u32_u24 v2, v106, s89, v18
	ds_read_b128 v[2:5], v2
	v_cndmask_b32_e32 v0, v174, v0, vcc
	v_lshlrev_b32_e32 v42, 2, v0
	v_and_b32_e32 v0, 7, v104
	v_cmp_eq_u32_e64 s[38:39], 0, v0
	s_waitcnt lgkmcnt(0)
	v_lshlrev_b32_e32 v6, 16, v2
	v_and_b32_e32 v7, 0xffff0000, v2
	v_lshlrev_b32_e32 v2, 16, v62
	v_mul_f32_e32 v10, 0xbfb8aa3b, v2
	v_exp_f32_e32 v10, v10
	v_lshl_add_u32 v0, s2, 7, v101
	v_pk_add_f32 v[10:11], v[10:11], 1.0 op_sel_hi:[1,0]
	s_nop 0
	v_div_scale_f32 v13, s[2:3], v11, v11, v12
	v_rcp_f32_e32 v14, v13
	s_nop 0
	v_fma_f32 v15, -v13, v14, 1.0
	v_fmac_f32_e32 v14, v15, v14
	v_div_scale_f32 v15, vcc, v12, v11, v12
	v_mul_f32_e32 v16, v15, v14
	v_fma_f32 v17, -v13, v16, v15
	v_fmac_f32_e32 v16, v17, v14
	v_fma_f32 v13, -v13, v16, v15
	v_div_fmas_f32 v13, v13, v14, v16
	v_div_fixup_f32 v11, v13, v11, v12
	v_div_scale_f32 v12, s[2:3], v10, v10, v2
	v_rcp_f32_e32 v13, v12
	s_nop 0
	v_fma_f32 v14, -v12, v13, 1.0
	v_fmac_f32_e32 v13, v14, v13
	v_div_scale_f32 v14, vcc, v2, v10, v2
	v_mul_f32_e32 v15, v14, v13
	v_fma_f32 v16, -v12, v15, v14
	v_fmac_f32_e32 v15, v16, v13
	v_fma_f32 v12, -v12, v15, v14
	v_div_fmas_f32 v12, v12, v13, v15
	v_lshlrev_b32_e32 v14, 16, v63
	v_and_b32_e32 v15, 0xffff0000, v63
	v_div_fixup_f32 v10, v12, v10, v2
	v_mul_f32_e32 v12, 0xbfb8aa3b, v14
	v_mul_f32_e32 v13, 0xbfb8aa3b, v15
	v_exp_f32_e32 v12, v12
	v_exp_f32_e32 v13, v13
	v_pk_mul_f32 v[10:11], v[10:11], v[6:7]
	v_lshlrev_b32_e32 v2, 16, v3
	v_and_b32_e32 v3, 0xffff0000, v3
	v_pk_add_f32 v[12:13], v[12:13], 1.0 op_sel_hi:[1,0]
	v_pk_mul_f32 v[6:7], v[10:11], v[10:11]
	v_div_scale_f32 v16, s[2:3], v13, v13, v15
	v_rcp_f32_e32 v17, v16
	v_add_f32_e32 v6, v6, v7
	v_fma_f32 v19, -v16, v17, 1.0
	v_fmac_f32_e32 v17, v19, v17
	v_div_scale_f32 v19, vcc, v15, v13, v15
	v_mul_f32_e32 v20, v19, v17
	v_fma_f32 v21, -v16, v20, v19
	v_fmac_f32_e32 v20, v21, v17
	v_fma_f32 v16, -v16, v20, v19
	v_div_fmas_f32 v16, v16, v17, v20
	v_div_fixup_f32 v13, v16, v13, v15
	v_div_scale_f32 v15, s[2:3], v12, v12, v14
	v_rcp_f32_e32 v16, v15
	s_nop 0
	v_fma_f32 v17, -v15, v16, 1.0
	v_fmac_f32_e32 v16, v17, v16
	v_div_scale_f32 v17, vcc, v14, v12, v14
	v_mul_f32_e32 v19, v17, v16
	v_fma_f32 v20, -v15, v19, v17
	v_fmac_f32_e32 v19, v20, v16
	v_fma_f32 v15, -v15, v19, v17
	v_div_fmas_f32 v15, v15, v16, v19
	v_div_fixup_f32 v12, v15, v12, v14
	v_lshlrev_b32_e32 v14, 16, v4
	v_and_b32_e32 v15, 0xffff0000, v4
	v_lshlrev_b32_e32 v4, 16, v64
	v_and_b32_e32 v19, 0xffff0000, v64
	v_mul_f32_e32 v16, 0xbfb8aa3b, v4
	v_mul_f32_e32 v17, 0xbfb8aa3b, v19
	v_exp_f32_e32 v16, v16
	v_exp_f32_e32 v17, v17
	v_pk_mul_f32 v[12:13], v[12:13], v[2:3]
	v_pk_add_f32 v[16:17], v[16:17], 1.0 op_sel_hi:[1,0]
	s_nop 0
	v_div_scale_f32 v20, s[2:3], v17, v17, v19
	v_rcp_f32_e32 v21, v20
	v_pk_mul_f32 v[2:3], v[12:13], v[12:13]
	v_fma_f32 v22, -v20, v21, 1.0
	v_fmac_f32_e32 v21, v22, v21
	v_div_scale_f32 v22, vcc, v19, v17, v19
	v_mul_f32_e32 v23, v22, v21
	v_fma_f32 v24, -v20, v23, v22
	v_fmac_f32_e32 v23, v24, v21
	v_fma_f32 v20, -v20, v23, v22
	v_div_fmas_f32 v20, v20, v21, v23
	v_div_fixup_f32 v17, v20, v17, v19
	v_div_scale_f32 v19, s[2:3], v16, v16, v4
	v_rcp_f32_e32 v20, v19
	v_add_f32_e32 v2, v2, v6
	v_add_f32_e32 v2, v3, v2
	v_fma_f32 v21, -v19, v20, 1.0
	v_fmac_f32_e32 v20, v21, v20
	v_div_scale_f32 v21, vcc, v4, v16, v4
	v_mul_f32_e32 v22, v21, v20
	v_fma_f32 v23, -v19, v22, v21
	v_fmac_f32_e32 v22, v23, v20
	v_fma_f32 v19, -v19, v22, v21
	v_div_fmas_f32 v19, v19, v20, v22
	v_div_fixup_f32 v16, v19, v16, v4
	v_lshlrev_b32_e32 v19, 16, v65
	v_and_b32_e32 v22, 0xffff0000, v65
	v_pk_mul_f32 v[14:15], v[16:17], v[14:15]
	v_mul_f32_e32 v16, 0xbfb8aa3b, v19
	v_mul_f32_e32 v17, 0xbfb8aa3b, v22
	v_exp_f32_e32 v16, v16
	v_exp_f32_e32 v17, v17
	v_pk_mul_f32 v[20:21], v[14:15], v[14:15]
	v_lshlrev_b32_e32 v4, 16, v5
	v_and_b32_e32 v5, 0xffff0000, v5
	v_pk_add_f32 v[16:17], v[16:17], 1.0 op_sel_hi:[1,0]
	v_add_f32_e32 v2, v20, v2
	v_div_scale_f32 v23, s[2:3], v17, v17, v22
	v_rcp_f32_e32 v24, v23
	v_add_f32_e32 v2, v21, v2
	v_fma_f32 v25, -v23, v24, 1.0
	v_fmac_f32_e32 v24, v25, v24
	v_div_scale_f32 v25, vcc, v22, v17, v22
	v_mul_f32_e32 v26, v25, v24
	v_fma_f32 v27, -v23, v26, v25
	v_fmac_f32_e32 v26, v27, v24
	v_fma_f32 v23, -v23, v26, v25
	v_div_fmas_f32 v23, v23, v24, v26
	v_div_fixup_f32 v17, v23, v17, v22
	v_div_scale_f32 v22, s[2:3], v16, v16, v19
	v_rcp_f32_e32 v23, v22
	s_nop 0
	v_fma_f32 v24, -v22, v23, 1.0
	v_fmac_f32_e32 v23, v24, v23
	v_div_scale_f32 v24, vcc, v19, v16, v19
	v_mul_f32_e32 v25, v24, v23
	v_fma_f32 v26, -v22, v25, v24
	v_fmac_f32_e32 v25, v26, v23
	v_fma_f32 v22, -v22, v25, v24
	v_div_fmas_f32 v22, v22, v23, v25
	v_div_fixup_f32 v16, v22, v16, v19
	v_pk_mul_f32 v[16:17], v[16:17], v[4:5]
	s_nop 0
	v_pk_mul_f32 v[4:5], v[16:17], v[16:17]
	s_nop 0
	v_add_f32_e32 v2, v4, v2
	v_add_f32_e32 v2, v5, v2
	s_nop 1
	v_add_f32_dpp v2, v2, v2 quad_perm:[1,0,3,2] row_mask:0xf bank_mask:0xf
	s_nop 1
	v_add_f32_dpp v2, v2, v2 quad_perm:[2,3,0,1] row_mask:0xf bank_mask:0xf
	s_nop 1
	v_add_f32_dpp v2, v2, v2 row_half_mirror row_mask:0xf bank_mask:0xf
	s_and_saveexec_b64 s[2:3], s[38:39]
	s_cbranch_execz .LBB0_246
	s_waitcnt lgkmcnt(0)
	v_lshl_add_u32 v3, v106, 2, v0
	ds_write_b32 v3, v2 offset:3072
.LBB0_246:
	s_or_b64 exec, exec, s[2:3]
	v_mul_u32_u24_e32 v2, 0x90, v106
	v_add_u32_e32 v34, v2, v18
	s_waitcnt lgkmcnt(0)
	ds_read_b128 v[2:5], v34 offset:1152
	v_and_b32_e32 v20, 0xffff0000, v58
	v_mul_f32_e32 v19, 0xbfb8aa3b, v20
	v_exp_f32_e32 v19, v19
	v_or_b32_e32 v44, 8, v106
	s_waitcnt lgkmcnt(0)
	v_lshlrev_b32_e32 v6, 16, v2
	v_and_b32_e32 v7, 0xffff0000, v2
	v_lshlrev_b32_e32 v2, 16, v58
	v_mul_f32_e32 v18, 0xbfb8aa3b, v2
	v_exp_f32_e32 v18, v18
	s_nop 0
	v_pk_add_f32 v[18:19], v[18:19], 1.0 op_sel_hi:[1,0]
	s_nop 0
	v_div_scale_f32 v21, s[2:3], v19, v19, v20
	v_rcp_f32_e32 v22, v21
	s_nop 0
	v_fma_f32 v23, -v21, v22, 1.0
	v_fmac_f32_e32 v22, v23, v22
	v_div_scale_f32 v23, vcc, v20, v19, v20
	v_mul_f32_e32 v24, v23, v22
	v_fma_f32 v25, -v21, v24, v23
	v_fmac_f32_e32 v24, v25, v22
	v_fma_f32 v21, -v21, v24, v23
	v_div_fmas_f32 v21, v21, v22, v24
	v_div_fixup_f32 v19, v21, v19, v20
	v_div_scale_f32 v20, s[2:3], v18, v18, v2
	v_rcp_f32_e32 v21, v20
	s_nop 0
	v_fma_f32 v22, -v20, v21, 1.0
	v_fmac_f32_e32 v21, v22, v21
	v_div_scale_f32 v22, vcc, v2, v18, v2
	v_mul_f32_e32 v23, v22, v21
	v_fma_f32 v24, -v20, v23, v22
	v_fmac_f32_e32 v23, v24, v21
	v_fma_f32 v20, -v20, v23, v22
	v_div_fmas_f32 v20, v20, v21, v23
	v_div_fixup_f32 v18, v20, v18, v2
	v_lshlrev_b32_e32 v22, 16, v59
	v_and_b32_e32 v23, 0xffff0000, v59
	v_pk_mul_f32 v[20:21], v[18:19], v[6:7]
	v_mul_f32_e32 v18, 0xbfb8aa3b, v22
	v_mul_f32_e32 v19, 0xbfb8aa3b, v23
	v_exp_f32_e32 v18, v18
	v_exp_f32_e32 v19, v19
	v_lshlrev_b32_e32 v2, 16, v3
	v_and_b32_e32 v3, 0xffff0000, v3
	v_pk_mul_f32 v[6:7], v[20:21], v[20:21]
	v_pk_add_f32 v[18:19], v[18:19], 1.0 op_sel_hi:[1,0]
	v_add_f32_e32 v6, v6, v7
	v_div_scale_f32 v24, s[2:3], v19, v19, v23
	v_rcp_f32_e32 v25, v24
	s_nop 0
	v_fma_f32 v26, -v24, v25, 1.0
	v_fmac_f32_e32 v25, v26, v25
	v_div_scale_f32 v26, vcc, v23, v19, v23
	v_mul_f32_e32 v27, v26, v25
	v_fma_f32 v28, -v24, v27, v26
	v_fmac_f32_e32 v27, v28, v25
	v_fma_f32 v24, -v24, v27, v26
	v_div_fmas_f32 v24, v24, v25, v27
	v_div_fixup_f32 v19, v24, v19, v23
	v_div_scale_f32 v23, s[2:3], v18, v18, v22
	v_rcp_f32_e32 v24, v23
	s_nop 0
	v_fma_f32 v25, -v23, v24, 1.0
	v_fmac_f32_e32 v24, v25, v24
	v_div_scale_f32 v25, vcc, v22, v18, v22
	v_mul_f32_e32 v26, v25, v24
	v_fma_f32 v27, -v23, v26, v25
	v_fmac_f32_e32 v26, v27, v24
	v_fma_f32 v23, -v23, v26, v25
	v_div_fmas_f32 v23, v23, v24, v26
	v_div_fixup_f32 v18, v23, v18, v22
	v_pk_mul_f32 v[24:25], v[18:19], v[2:3]
	v_lshlrev_b32_e32 v18, 16, v4
	v_and_b32_e32 v19, 0xffff0000, v4
	v_lshlrev_b32_e32 v4, 16, v60
	v_and_b32_e32 v26, 0xffff0000, v60
	v_mul_f32_e32 v22, 0xbfb8aa3b, v4
	v_mul_f32_e32 v23, 0xbfb8aa3b, v26
	v_exp_f32_e32 v22, v22
	v_exp_f32_e32 v23, v23
	v_pk_mul_f32 v[2:3], v[24:25], v[24:25]
	v_pk_add_f32 v[22:23], v[22:23], 1.0 op_sel_hi:[1,0]
	s_nop 0
	v_div_scale_f32 v27, s[2:3], v23, v23, v26
	v_rcp_f32_e32 v28, v27
	v_add_f32_e32 v2, v2, v6
	v_add_f32_e32 v2, v3, v2
	v_fma_f32 v29, -v27, v28, 1.0
	v_fmac_f32_e32 v28, v29, v28
	v_div_scale_f32 v29, vcc, v26, v23, v26
	v_mul_f32_e32 v30, v29, v28
	v_fma_f32 v31, -v27, v30, v29
	v_fmac_f32_e32 v30, v31, v28
	v_fma_f32 v27, -v27, v30, v29
	v_div_fmas_f32 v27, v27, v28, v30
	v_div_fixup_f32 v23, v27, v23, v26
	v_div_scale_f32 v26, s[2:3], v22, v22, v4
	v_rcp_f32_e32 v27, v26
	s_nop 0
	v_fma_f32 v28, -v26, v27, 1.0
	v_fmac_f32_e32 v27, v28, v27
	v_div_scale_f32 v28, vcc, v4, v22, v4
	v_mul_f32_e32 v29, v28, v27
	v_fma_f32 v30, -v26, v29, v28
	v_fmac_f32_e32 v29, v30, v27
	v_fma_f32 v26, -v26, v29, v28
	v_div_fmas_f32 v26, v26, v27, v29
	v_div_fixup_f32 v22, v26, v22, v4
	v_lshlrev_b32_e32 v26, 16, v61
	v_and_b32_e32 v27, 0xffff0000, v61
	v_pk_mul_f32 v[28:29], v[22:23], v[18:19]
	v_mul_f32_e32 v22, 0xbfb8aa3b, v26
	v_mul_f32_e32 v23, 0xbfb8aa3b, v27
	v_exp_f32_e32 v22, v22
	v_exp_f32_e32 v23, v23
	v_pk_mul_f32 v[18:19], v[28:29], v[28:29]
	v_lshlrev_b32_e32 v4, 16, v5
	v_and_b32_e32 v5, 0xffff0000, v5
	v_pk_add_f32 v[22:23], v[22:23], 1.0 op_sel_hi:[1,0]
	v_add_f32_e32 v2, v18, v2
	v_div_scale_f32 v30, s[2:3], v23, v23, v27
	v_rcp_f32_e32 v31, v30
	v_add_f32_e32 v2, v19, v2
	v_fma_f32 v32, -v30, v31, 1.0
	v_fmac_f32_e32 v31, v32, v31
	v_div_scale_f32 v32, vcc, v27, v23, v27
	v_mul_f32_e32 v33, v32, v31
	v_fma_f32 v35, -v30, v33, v32
	v_fmac_f32_e32 v33, v35, v31
	v_fma_f32 v30, -v30, v33, v32
	v_div_fmas_f32 v30, v30, v31, v33
	v_div_fixup_f32 v23, v30, v23, v27
	v_div_scale_f32 v27, s[2:3], v22, v22, v26
	v_rcp_f32_e32 v30, v27
	s_nop 0
	v_fma_f32 v31, -v27, v30, 1.0
	v_fmac_f32_e32 v30, v31, v30
	v_div_scale_f32 v31, vcc, v26, v22, v26
	v_mul_f32_e32 v32, v31, v30
	v_fma_f32 v33, -v27, v32, v31
	v_fmac_f32_e32 v32, v33, v30
	v_fma_f32 v27, -v27, v32, v31
	v_div_fmas_f32 v27, v27, v30, v32
	v_div_fixup_f32 v22, v27, v22, v26
	v_pk_mul_f32 v[32:33], v[22:23], v[4:5]
	s_nop 0
	v_pk_mul_f32 v[4:5], v[32:33], v[32:33]
	s_nop 0
	v_add_f32_e32 v2, v4, v2
	v_add_f32_e32 v2, v5, v2
	s_nop 1
	v_add_f32_dpp v2, v2, v2 quad_perm:[1,0,3,2] row_mask:0xf bank_mask:0xf
	s_nop 1
	v_add_f32_dpp v2, v2, v2 quad_perm:[2,3,0,1] row_mask:0xf bank_mask:0xf
	s_nop 1
	v_add_f32_dpp v2, v2, v2 row_half_mirror row_mask:0xf bank_mask:0xf
	s_and_saveexec_b64 s[2:3], s[38:39]
	s_cbranch_execz .LBB0_248
	s_waitcnt lgkmcnt(0)
	v_lshl_add_u32 v3, v44, 2, v0
	ds_write_b32 v3, v2 offset:3072
.LBB0_248:
	s_or_b64 exec, exec, s[2:3]
	s_waitcnt lgkmcnt(0)
	ds_read_b128 v[2:5], v34 offset:2304
	v_and_b32_e32 v22, 0xffff0000, v54
	v_mul_f32_e32 v19, 0xbfb8aa3b, v22
	v_exp_f32_e32 v19, v19
	v_or_b32_e32 v45, 16, v106
	s_waitcnt lgkmcnt(0)
	v_lshlrev_b32_e32 v6, 16, v2
	v_and_b32_e32 v7, 0xffff0000, v2
	v_lshlrev_b32_e32 v2, 16, v54
	v_mul_f32_e32 v18, 0xbfb8aa3b, v2
	v_exp_f32_e32 v18, v18
	s_nop 0
	v_pk_add_f32 v[18:19], v[18:19], 1.0 op_sel_hi:[1,0]
	s_nop 0
	v_div_scale_f32 v23, s[2:3], v19, v19, v22
	v_rcp_f32_e32 v26, v23
	s_nop 0
	v_fma_f32 v27, -v23, v26, 1.0
	v_fmac_f32_e32 v26, v27, v26
	v_div_scale_f32 v27, vcc, v22, v19, v22
	v_mul_f32_e32 v30, v27, v26
	v_fma_f32 v31, -v23, v30, v27
	v_fmac_f32_e32 v30, v31, v26
	v_fma_f32 v23, -v23, v30, v27
	v_div_fmas_f32 v23, v23, v26, v30
	v_div_fixup_f32 v19, v23, v19, v22
	v_div_scale_f32 v22, s[2:3], v18, v18, v2
	v_rcp_f32_e32 v23, v22
	s_nop 0
	v_fma_f32 v26, -v22, v23, 1.0
	v_fmac_f32_e32 v23, v26, v23
	v_div_scale_f32 v26, vcc, v2, v18, v2
	v_mul_f32_e32 v27, v26, v23
	v_fma_f32 v30, -v22, v27, v26
	v_fmac_f32_e32 v27, v30, v23
	v_fma_f32 v22, -v22, v27, v26
	v_div_fmas_f32 v22, v22, v23, v27
	v_lshlrev_b32_e32 v26, 16, v55
	v_and_b32_e32 v27, 0xffff0000, v55
	v_div_fixup_f32 v18, v22, v18, v2
	v_mul_f32_e32 v22, 0xbfb8aa3b, v26
	v_mul_f32_e32 v23, 0xbfb8aa3b, v27
	v_exp_f32_e32 v22, v22
	v_exp_f32_e32 v23, v23
	v_pk_mul_f32 v[18:19], v[18:19], v[6:7]
	v_lshlrev_b32_e32 v2, 16, v3
	v_and_b32_e32 v3, 0xffff0000, v3
	v_pk_add_f32 v[22:23], v[22:23], 1.0 op_sel_hi:[1,0]
	v_pk_mul_f32 v[6:7], v[18:19], v[18:19]
	v_div_scale_f32 v30, s[2:3], v23, v23, v27
	v_rcp_f32_e32 v31, v30
	v_add_f32_e32 v6, v6, v7
	v_fma_f32 v35, -v30, v31, 1.0
	v_fmac_f32_e32 v31, v35, v31
	v_div_scale_f32 v35, vcc, v27, v23, v27
	v_mul_f32_e32 v36, v35, v31
	v_fma_f32 v37, -v30, v36, v35
	v_fmac_f32_e32 v36, v37, v31
	v_fma_f32 v30, -v30, v36, v35
	v_div_fmas_f32 v30, v30, v31, v36
	v_div_fixup_f32 v23, v30, v23, v27
	v_div_scale_f32 v27, s[2:3], v22, v22, v26
	v_rcp_f32_e32 v30, v27
	s_nop 0
	v_fma_f32 v31, -v27, v30, 1.0
	v_fmac_f32_e32 v30, v31, v30
	v_div_scale_f32 v31, vcc, v26, v22, v26
	v_mul_f32_e32 v35, v31, v30
	v_fma_f32 v36, -v27, v35, v31
	v_fmac_f32_e32 v35, v36, v30
	v_fma_f32 v27, -v27, v35, v31
	v_div_fmas_f32 v27, v27, v30, v35
	v_div_fixup_f32 v22, v27, v22, v26
	v_lshlrev_b32_e32 v26, 16, v4
	v_and_b32_e32 v27, 0xffff0000, v4
	v_lshlrev_b32_e32 v4, 16, v56
	v_and_b32_e32 v35, 0xffff0000, v56
	v_mul_f32_e32 v30, 0xbfb8aa3b, v4
	v_mul_f32_e32 v31, 0xbfb8aa3b, v35
	v_exp_f32_e32 v30, v30
	v_exp_f32_e32 v31, v31
	v_pk_mul_f32 v[22:23], v[22:23], v[2:3]
	v_pk_add_f32 v[30:31], v[30:31], 1.0 op_sel_hi:[1,0]
	s_nop 0
	v_div_scale_f32 v36, s[2:3], v31, v31, v35
	v_rcp_f32_e32 v37, v36
	v_pk_mul_f32 v[2:3], v[22:23], v[22:23]
	v_fma_f32 v38, -v36, v37, 1.0
	v_fmac_f32_e32 v37, v38, v37
	v_div_scale_f32 v38, vcc, v35, v31, v35
	v_mul_f32_e32 v39, v38, v37
	v_fma_f32 v40, -v36, v39, v38
	v_fmac_f32_e32 v39, v40, v37
	v_fma_f32 v36, -v36, v39, v38
	v_div_fmas_f32 v36, v36, v37, v39
	v_div_fixup_f32 v31, v36, v31, v35
	v_div_scale_f32 v35, s[2:3], v30, v30, v4
	v_rcp_f32_e32 v36, v35
	v_add_f32_e32 v2, v2, v6
	v_add_f32_e32 v2, v3, v2
	v_fma_f32 v37, -v35, v36, 1.0
	v_fmac_f32_e32 v36, v37, v36
	v_div_scale_f32 v37, vcc, v4, v30, v4
	v_mul_f32_e32 v38, v37, v36
	v_fma_f32 v39, -v35, v38, v37
	v_fmac_f32_e32 v38, v39, v36
	v_fma_f32 v35, -v35, v38, v37
	v_div_fmas_f32 v35, v35, v36, v38
	v_div_fixup_f32 v30, v35, v30, v4
	v_lshlrev_b32_e32 v35, 16, v57
	v_and_b32_e32 v38, 0xffff0000, v57
	v_pk_mul_f32 v[26:27], v[30:31], v[26:27]
	v_mul_f32_e32 v30, 0xbfb8aa3b, v35
	v_mul_f32_e32 v31, 0xbfb8aa3b, v38
	v_exp_f32_e32 v30, v30
	v_exp_f32_e32 v31, v31
	v_pk_mul_f32 v[36:37], v[26:27], v[26:27]
	v_lshlrev_b32_e32 v4, 16, v5
	v_and_b32_e32 v5, 0xffff0000, v5
	v_pk_add_f32 v[30:31], v[30:31], 1.0 op_sel_hi:[1,0]
	v_add_f32_e32 v2, v36, v2
	v_div_scale_f32 v39, s[2:3], v31, v31, v38
	v_rcp_f32_e32 v40, v39
	v_add_f32_e32 v2, v37, v2
	v_fma_f32 v41, -v39, v40, 1.0
	v_fmac_f32_e32 v40, v41, v40
	v_div_scale_f32 v41, vcc, v38, v31, v38
	v_mul_f32_e32 v43, v41, v40
	v_fma_f32 v46, -v39, v43, v41
	v_fmac_f32_e32 v43, v46, v40
	v_fma_f32 v39, -v39, v43, v41
	v_div_fmas_f32 v39, v39, v40, v43
	v_div_fixup_f32 v31, v39, v31, v38
	v_div_scale_f32 v38, s[2:3], v30, v30, v35
	v_rcp_f32_e32 v39, v38
	s_nop 0
	v_fma_f32 v40, -v38, v39, 1.0
	v_fmac_f32_e32 v39, v40, v39
	v_div_scale_f32 v40, vcc, v35, v30, v35
	v_mul_f32_e32 v41, v40, v39
	v_fma_f32 v43, -v38, v41, v40
	v_fmac_f32_e32 v41, v43, v39
	v_fma_f32 v38, -v38, v41, v40
	v_div_fmas_f32 v38, v38, v39, v41
	v_div_fixup_f32 v30, v38, v30, v35
	v_pk_mul_f32 v[30:31], v[30:31], v[4:5]
	s_nop 0
	v_pk_mul_f32 v[4:5], v[30:31], v[30:31]
	s_nop 0
	v_add_f32_e32 v2, v4, v2
	v_add_f32_e32 v2, v5, v2
	s_nop 1
	v_add_f32_dpp v2, v2, v2 quad_perm:[1,0,3,2] row_mask:0xf bank_mask:0xf
	s_nop 1
	v_add_f32_dpp v2, v2, v2 quad_perm:[2,3,0,1] row_mask:0xf bank_mask:0xf
	s_nop 1
	v_add_f32_dpp v2, v2, v2 row_half_mirror row_mask:0xf bank_mask:0xf
	s_and_saveexec_b64 s[2:3], s[38:39]
	s_cbranch_execz .LBB0_250
	s_waitcnt lgkmcnt(0)
	v_lshl_add_u32 v3, v45, 2, v0
	ds_write_b32 v3, v2 offset:3072
.LBB0_250:
	s_or_b64 exec, exec, s[2:3]
	s_waitcnt lgkmcnt(0)
	ds_read_b128 v[2:5], v34 offset:3456
	v_and_b32_e32 v36, 0xffff0000, v50
	v_mul_f32_e32 v35, 0xbfb8aa3b, v36
	v_exp_f32_e32 v35, v35
	v_or_b32_e32 v46, 24, v106
	s_waitcnt lgkmcnt(0)
	v_lshlrev_b32_e32 v6, 16, v2
	v_and_b32_e32 v7, 0xffff0000, v2
	v_lshlrev_b32_e32 v2, 16, v50
	v_mul_f32_e32 v34, 0xbfb8aa3b, v2
	v_exp_f32_e32 v34, v34
	s_nop 0
	v_pk_add_f32 v[34:35], v[34:35], 1.0 op_sel_hi:[1,0]
	s_nop 0
	v_div_scale_f32 v37, s[2:3], v35, v35, v36
	v_rcp_f32_e32 v38, v37
	s_nop 0
	v_fma_f32 v39, -v37, v38, 1.0
	v_fmac_f32_e32 v38, v39, v38
	v_div_scale_f32 v39, vcc, v36, v35, v36
	v_mul_f32_e32 v40, v39, v38
	v_fma_f32 v41, -v37, v40, v39
	v_fmac_f32_e32 v40, v41, v38
	v_fma_f32 v37, -v37, v40, v39
	v_div_fmas_f32 v37, v37, v38, v40
	v_div_fixup_f32 v35, v37, v35, v36
	v_div_scale_f32 v36, s[2:3], v34, v34, v2
	v_rcp_f32_e32 v37, v36
	s_nop 0
	v_fma_f32 v38, -v36, v37, 1.0
	v_fmac_f32_e32 v37, v38, v37
	v_div_scale_f32 v38, vcc, v2, v34, v2
	v_mul_f32_e32 v39, v38, v37
	v_fma_f32 v40, -v36, v39, v38
	v_fmac_f32_e32 v39, v40, v37
	v_fma_f32 v36, -v36, v39, v38
	v_div_fmas_f32 v36, v36, v37, v39
	v_lshlrev_b32_e32 v38, 16, v51
	v_and_b32_e32 v39, 0xffff0000, v51
	v_div_fixup_f32 v34, v36, v34, v2
	v_mul_f32_e32 v36, 0xbfb8aa3b, v38
	v_mul_f32_e32 v37, 0xbfb8aa3b, v39
	v_exp_f32_e32 v36, v36
	v_exp_f32_e32 v37, v37
	v_pk_mul_f32 v[34:35], v[34:35], v[6:7]
	v_lshlrev_b32_e32 v2, 16, v3
	v_and_b32_e32 v3, 0xffff0000, v3
	v_pk_add_f32 v[36:37], v[36:37], 1.0 op_sel_hi:[1,0]
	v_pk_mul_f32 v[6:7], v[34:35], v[34:35]
	v_div_scale_f32 v40, s[2:3], v37, v37, v39
	v_rcp_f32_e32 v41, v40
	v_add_f32_e32 v6, v6, v7
	v_fma_f32 v43, -v40, v41, 1.0
	v_fmac_f32_e32 v41, v43, v41
	v_div_scale_f32 v43, vcc, v39, v37, v39
	v_mul_f32_e32 v47, v43, v41
	v_fma_f32 v48, -v40, v47, v43
	v_fmac_f32_e32 v47, v48, v41
	v_fma_f32 v40, -v40, v47, v43
	v_div_fmas_f32 v40, v40, v41, v47
	v_div_fixup_f32 v37, v40, v37, v39
	v_div_scale_f32 v39, s[2:3], v36, v36, v38
	v_rcp_f32_e32 v40, v39
	s_nop 0
	v_fma_f32 v41, -v39, v40, 1.0
	v_fmac_f32_e32 v40, v41, v40
	v_div_scale_f32 v41, vcc, v38, v36, v38
	v_mul_f32_e32 v43, v41, v40
	v_fma_f32 v47, -v39, v43, v41
	v_fmac_f32_e32 v43, v47, v40
	v_fma_f32 v39, -v39, v43, v41
	v_div_fmas_f32 v39, v39, v40, v43
	v_div_fixup_f32 v36, v39, v36, v38
	v_lshlrev_b32_e32 v38, 16, v4
	v_and_b32_e32 v39, 0xffff0000, v4
	v_lshlrev_b32_e32 v4, 16, v52
	v_and_b32_e32 v43, 0xffff0000, v52
	v_mul_f32_e32 v40, 0xbfb8aa3b, v4
	v_mul_f32_e32 v41, 0xbfb8aa3b, v43
	v_exp_f32_e32 v40, v40
	v_exp_f32_e32 v41, v41
	v_pk_mul_f32 v[36:37], v[36:37], v[2:3]
	v_pk_add_f32 v[40:41], v[40:41], 1.0 op_sel_hi:[1,0]
	s_nop 0
	v_div_scale_f32 v47, s[2:3], v41, v41, v43
	v_rcp_f32_e32 v48, v47
	v_pk_mul_f32 v[2:3], v[36:37], v[36:37]
	v_fma_f32 v49, -v47, v48, 1.0
	v_fmac_f32_e32 v48, v49, v48
	v_div_scale_f32 v49, vcc, v43, v41, v43
	v_mul_f32_e32 v50, v49, v48
	v_fma_f32 v51, -v47, v50, v49
	v_fmac_f32_e32 v50, v51, v48
	v_fma_f32 v47, -v47, v50, v49
	v_div_fmas_f32 v47, v47, v48, v50
	v_div_fixup_f32 v41, v47, v41, v43
	v_div_scale_f32 v43, s[2:3], v40, v40, v4
	v_rcp_f32_e32 v47, v43
	v_add_f32_e32 v2, v2, v6
	v_add_f32_e32 v2, v3, v2
	v_fma_f32 v48, -v43, v47, 1.0
	v_fmac_f32_e32 v47, v48, v47
	v_div_scale_f32 v48, vcc, v4, v40, v4
	v_mul_f32_e32 v49, v48, v47
	v_fma_f32 v50, -v43, v49, v48
	v_fmac_f32_e32 v49, v50, v47
	v_fma_f32 v43, -v43, v49, v48
	v_div_fmas_f32 v43, v43, v47, v49
	v_div_fixup_f32 v40, v43, v40, v4
	v_lshlrev_b32_e32 v43, 16, v53
	v_and_b32_e32 v47, 0xffff0000, v53
	v_pk_mul_f32 v[38:39], v[40:41], v[38:39]
	v_mul_f32_e32 v40, 0xbfb8aa3b, v43
	v_mul_f32_e32 v41, 0xbfb8aa3b, v47
	v_exp_f32_e32 v40, v40
	v_exp_f32_e32 v41, v41
	v_pk_mul_f32 v[48:49], v[38:39], v[38:39]
	v_lshlrev_b32_e32 v4, 16, v5
	v_and_b32_e32 v5, 0xffff0000, v5
	v_pk_add_f32 v[40:41], v[40:41], 1.0 op_sel_hi:[1,0]
	v_add_f32_e32 v2, v48, v2
	v_div_scale_f32 v50, s[2:3], v41, v41, v47
	v_rcp_f32_e32 v51, v50
	v_add_f32_e32 v2, v49, v2
	v_fma_f32 v52, -v50, v51, 1.0
	v_fmac_f32_e32 v51, v52, v51
	v_div_scale_f32 v52, vcc, v47, v41, v47
	v_mul_f32_e32 v53, v52, v51
	v_fma_f32 v54, -v50, v53, v52
	v_fmac_f32_e32 v53, v54, v51
	v_fma_f32 v50, -v50, v53, v52
	v_div_fmas_f32 v50, v50, v51, v53
	v_div_fixup_f32 v41, v50, v41, v47
	v_div_scale_f32 v47, s[2:3], v40, v40, v43
	v_rcp_f32_e32 v50, v47
	s_nop 0
	v_fma_f32 v51, -v47, v50, 1.0
	v_fmac_f32_e32 v50, v51, v50
	v_div_scale_f32 v51, vcc, v43, v40, v43
	v_mul_f32_e32 v52, v51, v50
	v_fma_f32 v53, -v47, v52, v51
	v_fmac_f32_e32 v52, v53, v50
	v_fma_f32 v47, -v47, v52, v51
	v_div_fmas_f32 v47, v47, v50, v52
	v_div_fixup_f32 v40, v47, v40, v43
	v_pk_mul_f32 v[40:41], v[40:41], v[4:5]
	s_nop 0
	v_pk_mul_f32 v[4:5], v[40:41], v[40:41]
	s_nop 0
	v_add_f32_e32 v2, v4, v2
	v_add_f32_e32 v2, v5, v2
	s_nop 1
	v_add_f32_dpp v2, v2, v2 quad_perm:[1,0,3,2] row_mask:0xf bank_mask:0xf
	s_nop 1
	v_add_f32_dpp v2, v2, v2 quad_perm:[2,3,0,1] row_mask:0xf bank_mask:0xf
	s_nop 1
	v_add_f32_dpp v2, v2, v2 row_half_mirror row_mask:0xf bank_mask:0xf
	s_and_saveexec_b64 s[2:3], s[38:39]
	s_cbranch_execz .LBB0_252
	s_waitcnt lgkmcnt(0)
	v_lshl_add_u32 v0, v46, 2, v0
	ds_write_b32 v0, v2 offset:3072
